# cross attention: K chunk staged once per workgroup in (static) LDS with full-line cooperative loads and XOR swizzle instead of per-wave 16-row x 64B fragment loads
# speedup vs baseline: 1.1990x; 1.0294x over previous
; #define CR_KLOAD(cc) do { _Pragma("unroll") for (int kt = 0; kt < 2; ++kt) { const bf16* kr = kb + (size_t)(32 * (cc) + 16 * kt + i) * 2048; _Pragma("unroll") for (int ks = 0; ks < KS; ++ks) kf[kt][ks] = *(const bf16x8*)(kr + ks * 32 + g * 8); } } while (0)
; __device__ __forceinline__ void cross_phase(const Ctx& C, const bf16* Q, const bf16* KV  , bf16* O) {
;     ...
;         for (int tt = 0; tt < 8; ++tt) {
;             int l2_ = lane; asm volatile("" : "+v"(l2_)); const int i = l2_ & 15, g = l2_ >> 4;
;             const int t0 = half * 1024 + (C.wave * 8 + tt) * 16;
;             const bf16* qr = Q + (size_t)(b * SEQ + t0 + i) * DM + hd * 256;
;             bf16x8 qf[KS];
; #pragma unroll
;             for (int ks = 0; ks < KS; ++ks) qf[ks] = *(const bf16x8*)(qr + ks * 32 + g * 8);
;             f32x4 oacc[DT];
; #pragma unroll
;             for (int dt = 0; dt < DT; ++dt) oacc[dt] = (f32x4){0.f, 0.f, 0.f, 0.f};
;             float m_run = -1e30f, l_run = 0.f;
;             bf16x8 kf[2][KS];
;     ...
;             for (int c = 0; c < MEML / 32; ++c) {
;                 CR_KLOAD(c);
;                 f32x4 st[2];
; #pragma unroll
;                 for (int kt = 0; kt < 2; ++kt) { st[kt] = (f32x4){0.f, 0.f, 0.f, 0.f};
; #pragma unroll
;                     for (int ks = 0; ks < KS; ++ks) st[kt] = __builtin_amdgcn_mfma_f32_16x16x32_bf16(kf[kt][ks], qf[ks], st[kt], 0, 0, 0); }
.LBB0_292:
	v_mov_b32_e32 v34, v139
	s_lshl_b32 s8, s12, 4
	s_add_i32 s8, s11, s8
	v_and_b32_e32 v35, 15, v34
	v_ashrrev_i32_e32 v133, 4, v34
	v_or_b32_e32 v0, s8, v35
	v_ashrrev_i32_e32 v1, 31, v0
	v_lshlrev_b32_e32 v2, 3, v133
	v_lshlrev_b64 v[134:135], 10, v[0:1]
	v_lshlrev_b64 v[0:1], 11, v[0:1]
	v_ashrrev_i32_e32 v3, 31, v2
	v_lshl_add_u64 v[0:1], s[0:1], 0, v[0:1]
	v_lshlrev_b64 v[32:33], 1, v[2:3]
	v_lshl_add_u64 v[28:29], v[0:1], 0, v[32:33]
	global_load_dwordx4 v[0:3], v[28:29], off
	global_load_dwordx4 v[4:7], v[28:29], off offset:64
	global_load_dwordx4 v[8:11], v[28:29], off offset:128
	global_load_dwordx4 v[12:15], v[28:29], off offset:192
	global_load_dwordx4 v[16:19], v[28:29], off offset:256
	global_load_dwordx4 v[20:23], v[28:29], off offset:320
	global_load_dwordx4 v[24:27], v[28:29], off offset:384
	s_nop 0
	global_load_dwordx4 v[28:31], v[28:29], off offset:448
	v_and_b32_e32 v37, 64, v181
	v_xor_b32_e32 v36, 16, v181
	v_add_u32_e32 v37, 64, v37
	v_cmp_lt_i32_e32 vcc, v36, v37
	s_movk_i32 s8, 0x840
	v_lshlrev_b32_e32 v136, 12, v35
	v_cndmask_b32_e32 v36, v181, v36, vcc
	v_lshlrev_b32_e32 v159, 2, v36
	v_xor_b32_e32 v36, 32, v181
	v_cmp_lt_i32_e32 vcc, v36, v37
	v_mul_lo_u32 v37, v133, s8
	v_readlane_b32 s8, v247, 37
	v_cndmask_b32_e32 v36, v181, v36, vcc
	v_lshlrev_b32_e32 v160, 2, v36
	v_bfe_u32 v36, v34, 2, 2
	v_and_b32_e32 v34, 3, v34
	v_add_u32_e32 v37, s8, v37
	v_mul_u32_u24_e32 v36, 0x210, v36
	v_lshlrev_b32_e32 v34, 3, v34
	v_lshl_add_u64 v[32:33], v[136:137], 0, v[32:33]
	v_mov_b32_e32 v162, 0
	v_add3_u32 v161, v37, v36, v34
	v_lshl_add_u64 v[142:143], s[6:7], 0, v[32:33]
	v_mov_b32_e32 v72, 0xf149f2ca
	s_mov_b64 s[8:9], 0
	v_mov_b32_e32 v32, 0
	v_mov_b32_e32 v33, v162
	v_mov_b32_e32 v34, v162
	v_mov_b32_e32 v35, v162
	v_mov_b32_e32 v36, 0
	v_mov_b32_e32 v37, v162
	v_mov_b32_e32 v38, v162
	v_mov_b32_e32 v39, v162
	v_mov_b32_e32 v40, 0
	v_mov_b32_e32 v41, v162
	v_mov_b32_e32 v42, v162
	v_mov_b32_e32 v43, v162
	v_mov_b32_e32 v48, 0
	v_mov_b32_e32 v49, v162
	v_mov_b32_e32 v50, v162
	v_mov_b32_e32 v51, v162
	v_mov_b32_e32 v44, 0
	v_mov_b32_e32 v45, v162
	v_mov_b32_e32 v46, v162
	v_mov_b32_e32 v47, v162
	v_mov_b32_e32 v68, 0
	v_mov_b32_e32 v69, v162
	v_mov_b32_e32 v70, v162
	v_mov_b32_e32 v71, v162
	v_mov_b32_e32 v76, 0
	v_mov_b32_e32 v77, v162
	v_mov_b32_e32 v78, v162
	v_mov_b32_e32 v79, v162
	v_mov_b32_e32 v96, 0
	v_mov_b32_e32 v97, v162
	v_mov_b32_e32 v98, v162
	v_mov_b32_e32 v99, v162
	v_mov_b32_e32 v80, 0
	v_mov_b32_e32 v81, v162
	v_mov_b32_e32 v82, v162
	v_mov_b32_e32 v83, v162
	v_mov_b32_e32 v84, 0
	v_mov_b32_e32 v85, v162
	v_mov_b32_e32 v86, v162
	v_mov_b32_e32 v87, v162
	v_mov_b32_e32 v88, 0
	v_mov_b32_e32 v89, v162
	v_mov_b32_e32 v90, v162
	v_mov_b32_e32 v91, v162
	v_mov_b32_e32 v92, 0
	v_mov_b32_e32 v93, v162
	v_mov_b32_e32 v94, v162
	v_mov_b32_e32 v95, v162
	v_mov_b32_e32 v52, 0
	v_mov_b32_e32 v53, v162
	v_mov_b32_e32 v54, v162
	v_mov_b32_e32 v55, v162
	v_mov_b32_e32 v56, 0
	v_mov_b32_e32 v57, v162
	v_mov_b32_e32 v58, v162
	v_mov_b32_e32 v59, v162
	v_mov_b32_e32 v60, 0
	v_mov_b32_e32 v61, v162
	v_mov_b32_e32 v62, v162
	v_mov_b32_e32 v63, v162
	v_mov_b32_e32 v64, 0
	v_mov_b32_e32 v65, v162
	v_mov_b32_e32 v66, v162
	v_mov_b32_e32 v67, v162
	s_cmp_eq_u32 s96, 0x100
	s_cbranch_scc1 .Lcr_pre
.LBB0_293:
	v_lshl_add_u64 v[74:75], v[142:143], 0, s[8:9]
	s_mov_b32 s13, 0x11600000
	v_mov_b32_e32 v164, v162
	v_add_co_u32_e32 v162, vcc, s13, v74
	s_mov_b32 s13, 0x11610000
	s_nop 0
	v_addc_co_u32_e32 v163, vcc, 0, v75, vcc
	global_load_dwordx4 v[166:169], v[162:163], off
	global_load_dwordx4 v[170:173], v[162:163], off offset:64
	global_load_dwordx4 v[190:193], v[162:163], off offset:128
	global_load_dwordx4 v[194:197], v[162:163], off offset:192
	global_load_dwordx4 v[198:201], v[162:163], off offset:256
	global_load_dwordx4 v[202:205], v[162:163], off offset:320
	global_load_dwordx4 v[206:209], v[162:163], off offset:384
	global_load_dwordx4 v[210:213], v[162:163], off offset:448
	v_add_co_u32_e32 v74, vcc, s13, v74
	s_add_u32 s8, s8, 0x20000
	s_nop 0
	v_addc_co_u32_e32 v75, vcc, 0, v75, vcc
	global_load_dwordx4 v[214:217], v[74:75], off
	global_load_dwordx4 v[218:221], v[74:75], off offset:64
	global_load_dwordx4 v[222:225], v[74:75], off offset:128
	global_load_dwordx4 v[226:229], v[74:75], off offset:192
	global_load_dwordx4 v[230:233], v[74:75], off offset:256
	global_load_dwordx4 v[234:237], v[74:75], off offset:320
	global_load_dwordx4 v[238:241], v[74:75], off offset:384
	global_load_dwordx4 v[242:245], v[74:75], off offset:448
	s_addc_u32 s9, s9, 0
	s_cmp_lg_u32 s8, 0x100000
	s_waitcnt vmcnt(15)
	v_mfma_f32_16x16x32_bf16 v[166:169], v[166:169], v[0:3], 0
	s_waitcnt vmcnt(14)
	v_mfma_f32_16x16x32_bf16 v[166:169], v[170:173], v[4:7], v[166:169]
	s_waitcnt vmcnt(7)
	v_mfma_f32_16x16x32_bf16 v[170:173], v[214:217], v[0:3], 0
	s_waitcnt vmcnt(6)
	v_mfma_f32_16x16x32_bf16 v[170:173], v[218:221], v[4:7], v[170:173]
	v_mfma_f32_16x16x32_bf16 v[166:169], v[190:193], v[8:11], v[166:169]
	s_waitcnt vmcnt(5)
	v_mfma_f32_16x16x32_bf16 v[170:173], v[222:225], v[8:11], v[170:173]
	v_mfma_f32_16x16x32_bf16 v[166:169], v[194:197], v[12:15], v[166:169]
	s_waitcnt vmcnt(4)
	v_mfma_f32_16x16x32_bf16 v[170:173], v[226:229], v[12:15], v[170:173]
	v_mfma_f32_16x16x32_bf16 v[166:169], v[198:201], v[16:19], v[166:169]
	s_waitcnt vmcnt(3)
	v_mfma_f32_16x16x32_bf16 v[170:173], v[230:233], v[16:19], v[170:173]
	v_mfma_f32_16x16x32_bf16 v[166:169], v[202:205], v[20:23], v[166:169]
	s_waitcnt vmcnt(2)
	v_mfma_f32_16x16x32_bf16 v[170:173], v[234:237], v[20:23], v[170:173]
	v_mfma_f32_16x16x32_bf16 v[166:169], v[206:209], v[24:27], v[166:169]
	s_waitcnt vmcnt(1)
; __device__ __forceinline__ unsigned pk2(float lo, float hi) { return f2bf(lo) | (f2bf(hi) << 16); }
; __device__ __forceinline__ void cross_phase(const Ctx& C, const bf16* Q, const bf16* KV  , bf16* O) {
;     ...
;                 float pv[8];
; #pragma unroll
;                 for (int kt = 0; kt < 2; ++kt)
; #pragma unroll
;                     for (int j = 0; j < 4; ++j) pv[kt * 4 + j] = st[kt][j] * (0.0625f * LOG2E);
;                 float cm = pv[0];
; #pragma unroll
;                 for (int r = 1; r < 8; ++r) cm = fmaxf(cm, pv[r]);
;                 cm = fmaxf(cm, __shfl_xor(cm, 16)); cm = fmaxf(cm, __shfl_xor(cm, 32));
;                 const float mn = fmaxf(m_run, cm), sc = exp2f(m_run - mn);
;                 float ls = 0.f;
; #pragma unroll
;                 for (int r = 0; r < 8; ++r) { pv[r] = exp2f(pv[r] - mn); ls += pv[r]; }
;                 ls += __shfl_xor(ls, 16); ls += __shfl_xor(ls, 32);
;                 l_run = l_run * sc + ls; m_run = mn;
; #pragma unroll
;                 for (int dt = 0; dt < DT; ++dt) oacc[dt] = oacc[dt] * sc;
;                 bf16x8 pb; { v4u t; t.x = pk2(pv[0], pv[1]); t.y = pk2(pv[2], pv[3]); t.z = pk2(pv[4], pv[5]); t.w = pk2(pv[6], pv[7]); pb = __builtin_bit_cast(bf16x8, t); }
; #pragma unroll
;                 for (int d4 = 0; d4 < DT; d4 += 4) { bf16x8 vf4[4]; read_vfrags4_trp<P>(vs + (32 * c) * P + 16 * d4, i, g, vf4);
; #pragma unroll
;                     for (int dt = 0; dt < 4; ++dt) oacc[d4 + dt] = __builtin_amdgcn_mfma_f32_16x16x32_bf16(vf4[dt], pb, oacc[d4 + dt], 0, 0, 0); }
	v_mfma_f32_16x16x32_bf16 v[170:173], v[238:241], v[24:27], v[170:173]
	v_mfma_f32_16x16x32_bf16 v[166:169], v[210:213], v[28:31], v[166:169]
	s_waitcnt vmcnt(0)
	v_mfma_f32_16x16x32_bf16 v[170:173], v[242:245], v[28:31], v[170:173]
	s_nop 5
	v_mul_f32_e32 v73, 0x3db8aa3b, v166
	v_mul_f32_e32 v74, 0x3db8aa3b, v167
	v_mul_f32_e32 v75, 0x3db8aa3b, v168
	v_mul_f32_e32 v136, 0x3db8aa3b, v169
	v_max_f32_e32 v73, v73, v74
	v_mul_f32_e32 v162, 0x3db8aa3b, v170
	v_mul_f32_e32 v163, 0x3db8aa3b, v171
	v_max3_f32 v73, v73, v75, v136
	v_mul_f32_e32 v165, 0x3db8aa3b, v172
	v_mul_f32_e32 v174, 0x3db8aa3b, v173
	v_max3_f32 v73, v73, v162, v163
	v_max3_f32 v73, v73, v165, v174
	ds_bpermute_b32 v74, v159, v73
	v_add_u32_e32 v174, 0xfffffe80, v161
	s_waitcnt lgkmcnt(0)
	v_max_f32_e32 v74, v74, v74
	v_max_f32_e32 v73, v73, v74
	ds_bpermute_b32 v74, v160, v73
	s_waitcnt lgkmcnt(0)
	v_max3_f32 v163, v72, v73, v74
	v_fma_f32 v73, v166, s55, -v163
	v_fma_f32 v136, v168, s55, -v163
	v_sub_f32_e32 v72, v72, v163
	v_exp_f32_e32 v73, v73
	v_fma_f32 v74, v167, s55, -v163
	s_nop 1
	v_exp_f32_e32 v74, v74
	s_nop 0
	v_exp_f32_e32 v136, v136
	v_add_f32_e32 v75, v73, v74
	v_mov_b32_e32 v165, v136
	v_fma_f32 v136, v169, s55, -v163
	v_add_f32_e32 v75, v165, v75
	s_nop 0
	v_exp_f32_e32 v136, v136
	s_nop 0
	v_mov_b32_e32 v166, v136
	v_fma_f32 v136, v170, s55, -v163
	v_add_f32_e32 v75, v166, v75
	s_nop 0
	v_exp_f32_e32 v136, v136
	s_nop 0
	v_mov_b32_e32 v167, v136
	v_fma_f32 v136, v171, s55, -v163
	v_add_f32_e32 v75, v167, v75
	v_bfe_u32 v171, v166, 16, 1
	v_exp_f32_e32 v136, v136
	v_add3_u32 v166, v166, v171, s86
	v_mov_b32_e32 v168, v136
	v_fma_f32 v136, v172, s55, -v163
	v_add_f32_e32 v75, v168, v75
	v_bfe_u32 v172, v74, 16, 1
	v_exp_f32_e32 v136, v136
	v_add3_u32 v172, v74, v172, s86
	v_mov_b32_e32 v169, v136
	v_fma_f32 v136, v173, s55, -v163
	v_add_f32_e32 v75, v169, v75
	v_bfe_u32 v171, v169, 16, 1
	v_exp_f32_e32 v136, v136
	v_add3_u32 v169, v169, v171, s86
	v_mov_b32_e32 v170, v136
	v_exp_f32_e32 v72, v72
	v_add_f32_e32 v75, v170, v75
	v_mov_b32_e32 v136, v72
	ds_bpermute_b32 v72, v159, v75
	v_pk_mul_f32 v[98:99], v[98:99], v[136:137] op_sel_hi:[1,0]
	v_pk_mul_f32 v[96:97], v[96:97], v[136:137] op_sel_hi:[1,0]
	v_pk_mul_f32 v[78:79], v[78:79], v[136:137] op_sel_hi:[1,0]
	v_pk_mul_f32 v[76:77], v[76:77], v[136:137] op_sel_hi:[1,0]
	s_waitcnt lgkmcnt(0)
	v_add_f32_e32 v72, v75, v72
	ds_bpermute_b32 v75, v160, v72
	v_pk_mul_f32 v[70:71], v[70:71], v[136:137] op_sel_hi:[1,0]
	v_pk_mul_f32 v[68:69], v[68:69], v[136:137] op_sel_hi:[1,0]
	v_pk_mul_f32 v[46:47], v[46:47], v[136:137] op_sel_hi:[1,0]
	v_pk_mul_f32 v[44:45], v[44:45], v[136:137] op_sel_hi:[1,0]
	s_waitcnt lgkmcnt(0)
	v_add_f32_e32 v162, v72, v75
	v_bfe_u32 v72, v170, 16, 1
	v_bfe_u32 v75, v168, 16, 1
	v_add3_u32 v74, v168, v75, s86
	v_add3_u32 v72, v170, v72, s86
	v_bfe_u32 v75, v73, 16, 1
	v_bfe_u32 v168, v165, 16, 1
	v_bfe_u32 v170, v167, 16, 1
	v_add3_u32 v167, v167, v170, s86
	v_add3_u32 v165, v165, v168, s86
	v_add3_u32 v73, v73, v75, s86
	v_lshrrev_b32_e32 v168, 16, v73
	v_lshrrev_b32_e32 v73, 16, v165
	v_lshrrev_b32_e32 v165, 16, v167
	v_lshrrev_b32_e32 v75, 16, v169
	v_and_or_b32 v75, v72, s85, v75
	v_and_or_b32 v74, v74, s85, v165
	v_and_or_b32 v73, v166, s85, v73
	v_and_or_b32 v72, v172, s85, v168
	v_add_u32_e32 v165, 0xffffdd80, v161
	ds_read_b64_tr_b16 v[194:195], v165
	ds_read_b64_tr_b16 v[190:191], v165 offset:32
	ds_read_b64_tr_b16 v[170:171], v165 offset:64
	ds_read_b64_tr_b16 v[166:167], v165 offset:96
	ds_read_b64_tr_b16 v[196:197], v174
	ds_read_b64_tr_b16 v[192:193], v174 offset:32
	ds_read_b64_tr_b16 v[172:173], v174 offset:64
	ds_read_b64_tr_b16 v[168:169], v174 offset:96
	s_waitcnt lgkmcnt(0)
	v_pk_mul_f32 v[50:51], v[50:51], v[136:137] op_sel_hi:[1,0]
	v_pk_mul_f32 v[48:49], v[48:49], v[136:137] op_sel_hi:[1,0]
	v_pk_mul_f32 v[42:43], v[42:43], v[136:137] op_sel_hi:[1,0]
	v_pk_mul_f32 v[40:41], v[40:41], v[136:137] op_sel_hi:[1,0]
	v_pk_mul_f32 v[38:39], v[38:39], v[136:137] op_sel_hi:[1,0]
	v_pk_mul_f32 v[36:37], v[36:37], v[136:137] op_sel_hi:[1,0]
	v_pk_mul_f32 v[34:35], v[34:35], v[136:137] op_sel_hi:[1,0]
	v_pk_mul_f32 v[32:33], v[32:33], v[136:137] op_sel_hi:[1,0]
	v_mfma_f32_16x16x32_bf16 v[96:99], v[194:197], v[72:75], v[96:99]
	v_add_u32_e32 v165, 0xffffde00, v161
	v_add_u32_e32 v174, 0xffffff00, v161
	v_pk_mul_f32 v[82:83], v[82:83], v[136:137] op_sel_hi:[1,0]
	v_mfma_f32_16x16x32_bf16 v[76:79], v[190:193], v[72:75], v[76:79]
	v_mul_f32_e64 v80, v80, v136
	v_mul_f32_e64 v81, v81, v136
	v_pk_mul_f32 v[86:87], v[86:87], v[136:137] op_sel_hi:[1,0]
	v_pk_mul_f32 v[84:85], v[84:85], v[136:137] op_sel_hi:[1,0]
	v_mfma_f32_16x16x32_bf16 v[68:71], v[170:173], v[72:75], v[68:71]
	v_mul_f32_e64 v90, v90, v136
	v_mul_f32_e64 v91, v91, v136
	v_pk_mul_f32 v[88:89], v[88:89], v[136:137] op_sel_hi:[1,0]
	v_pk_mul_f32 v[94:95], v[94:95], v[136:137] op_sel_hi:[1,0]
	v_mfma_f32_16x16x32_bf16 v[44:47], v[166:169], v[72:75], v[44:47]
	ds_read_b64_tr_b16 v[194:195], v165
	ds_read_b64_tr_b16 v[190:191], v165 offset:32
	ds_read_b64_tr_b16 v[170:171], v165 offset:64
	ds_read_b64_tr_b16 v[166:167], v165 offset:96
	ds_read_b64_tr_b16 v[196:197], v174
	ds_read_b64_tr_b16 v[192:193], v174 offset:32
	ds_read_b64_tr_b16 v[172:173], v174 offset:64
	ds_read_b64_tr_b16 v[168:169], v174 offset:96
	s_waitcnt lgkmcnt(0)
; __device__ __forceinline__ unsigned pk2(float lo, float hi) { return f2bf(lo) | (f2bf(hi) << 16); }
; #define CR_KLOAD(cc) do { _Pragma("unroll") for (int kt = 0; kt < 2; ++kt) { const bf16* kr = kb + (size_t)(32 * (cc) + 16 * kt + i) * 2048; _Pragma("unroll") for (int ks = 0; ks < KS; ++ks) kf[kt][ks] = *(const bf16x8*)(kr + ks * 32 + g * 8); } } while (0)
; __device__ __forceinline__ void cross_phase(const Ctx& C, const bf16* Q, const bf16* KV  , bf16* O) {
;     ...
;             for (int c = 0; c < MEML / 32; ++c) {
;                 CR_KLOAD(c);
;                 f32x4 st[2];
; #pragma unroll
;                 for (int kt = 0; kt < 2; ++kt) { st[kt] = (f32x4){0.f, 0.f, 0.f, 0.f};
; #pragma unroll
;                     for (int ks = 0; ks < KS; ++ks) st[kt] = __builtin_amdgcn_mfma_f32_16x16x32_bf16(kf[kt][ks], qf[ks], st[kt], 0, 0, 0); }
;     ...
;                 for (int dt = 0; dt < DT; ++dt) oacc[dt] = oacc[dt] * sc;
;                 bf16x8 pb; { v4u t; t.x = pk2(pv[0], pv[1]); t.y = pk2(pv[2], pv[3]); t.z = pk2(pv[4], pv[5]); t.w = pk2(pv[6], pv[7]); pb = __builtin_bit_cast(bf16x8, t); }
; #pragma unroll
;                 for (int d4 = 0; d4 < DT; d4 += 4) { bf16x8 vf4[4]; read_vfrags4_trp<P>(vs + (32 * c) * P + 16 * d4, i, g, vf4);
; #pragma unroll
;                     for (int dt = 0; dt < 4; ++dt) oacc[d4 + dt] = __builtin_amdgcn_mfma_f32_16x16x32_bf16(vf4[dt], pb, oacc[d4 + dt], 0, 0, 0); }
	v_mul_f32_e64 v92, v92, v136
	v_mul_f32_e64 v93, v93, v136
	v_pk_mul_f32 v[54:55], v[54:55], v[136:137] op_sel_hi:[1,0]
	v_pk_mul_f32 v[52:53], v[52:53], v[136:137] op_sel_hi:[1,0]
	v_pk_mul_f32 v[58:59], v[58:59], v[136:137] op_sel_hi:[1,0]
	v_pk_mul_f32 v[56:57], v[56:57], v[136:137] op_sel_hi:[1,0]
	v_pk_mul_f32 v[62:63], v[62:63], v[136:137] op_sel_hi:[1,0]
	v_pk_mul_f32 v[60:61], v[60:61], v[136:137] op_sel_hi:[1,0]
	v_pk_mul_f32 v[66:67], v[66:67], v[136:137] op_sel_hi:[1,0]
	v_pk_mul_f32 v[64:65], v[64:65], v[136:137] op_sel_hi:[1,0]
	v_mfma_f32_16x16x32_bf16 v[48:51], v[194:197], v[72:75], v[48:51]
	v_add_u32_e32 v165, 0xffffde80, v161
	v_add_u32_e32 v174, 0xffffff80, v161
	v_fmac_f32_e32 v162, v164, v136
	v_mfma_f32_16x16x32_bf16 v[40:43], v[190:193], v[72:75], v[40:43]
	v_mfma_f32_16x16x32_bf16 v[36:39], v[170:173], v[72:75], v[36:39]
	v_mfma_f32_16x16x32_bf16 v[32:35], v[166:169], v[72:75], v[32:35]
	ds_read_b64_tr_b16 v[194:195], v165
	ds_read_b64_tr_b16 v[190:191], v165 offset:32
	ds_read_b64_tr_b16 v[170:171], v165 offset:64
	ds_read_b64_tr_b16 v[166:167], v165 offset:96
	ds_read_b64_tr_b16 v[196:197], v174
	ds_read_b64_tr_b16 v[192:193], v174 offset:32
	ds_read_b64_tr_b16 v[172:173], v174 offset:64
	ds_read_b64_tr_b16 v[168:169], v174 offset:96
	s_waitcnt lgkmcnt(0)
	v_add_u32_e32 v165, 0xffffdf00, v161
	v_mfma_f32_16x16x32_bf16 v[80:83], v[194:197], v[72:75], v[80:83]
	v_mfma_f32_16x16x32_bf16 v[84:87], v[190:193], v[72:75], v[84:87]
	v_mfma_f32_16x16x32_bf16 v[88:91], v[170:173], v[72:75], v[88:91]
	v_mfma_f32_16x16x32_bf16 v[92:95], v[166:169], v[72:75], v[92:95]
	ds_read_b64_tr_b16 v[194:195], v165
	ds_read_b64_tr_b16 v[190:191], v165 offset:32
	ds_read_b64_tr_b16 v[170:171], v165 offset:64
	ds_read_b64_tr_b16 v[166:167], v165 offset:96
	ds_read_b64_tr_b16 v[196:197], v161
	ds_read_b64_tr_b16 v[192:193], v161 offset:32
	ds_read_b64_tr_b16 v[172:173], v161 offset:64
	ds_read_b64_tr_b16 v[168:169], v161 offset:96
	s_waitcnt lgkmcnt(0)
	v_add_u32_e32 v161, 0x4200, v161
	v_mfma_f32_16x16x32_bf16 v[52:55], v[194:197], v[72:75], v[52:55]
	v_mfma_f32_16x16x32_bf16 v[56:59], v[190:193], v[72:75], v[56:59]
	v_mfma_f32_16x16x32_bf16 v[60:63], v[170:173], v[72:75], v[60:63]
	v_mfma_f32_16x16x32_bf16 v[64:67], v[166:169], v[72:75], v[64:67]
	v_mov_b32_e32 v72, v163
	s_cbranch_scc1 .LBB0_293
	s_branch .Lcr_after
.Lcr_pre:
	v_lshrrev_b32_e32 v100, 5, v176
	v_and_b32_e32 v101, 31, v176
	v_lshlrev_b32_e32 v118, 12, v100
	v_lshl_add_u32 v118, v101, 4, v118
	v_mov_b32_e32 v119, 0
	v_lshl_add_u64 v[116:117], s[6:7], 0, v[118:119]
	v_xor_b32_e32 v103, v101, v100
	v_lshlrev_b32_e32 v103, 4, v103
	v_lshl_add_u32 v103, v100, 9, v103
	v_add_u32_e32 v103, 0x24000, v103
	v_and_b32_e32 v104, 15, v177
	v_lshrrev_b32_e32 v105, 4, v177
	v_add_u32_e32 v106, 0, v105
	v_xor_b32_e32 v106, v106, v104
	v_lshlrev_b32_e32 v106, 4, v106
	v_lshl_add_u32 v108, v104, 9, v106
	v_add_u32_e32 v108, 0x24000, v108
	v_add_u32_e32 v106, 4, v105
	v_xor_b32_e32 v106, v106, v104
	v_lshlrev_b32_e32 v106, 4, v106
	v_lshl_add_u32 v109, v104, 9, v106
	v_add_u32_e32 v109, 0x24000, v109
	v_add_u32_e32 v106, 8, v105
	v_xor_b32_e32 v106, v106, v104
	v_lshlrev_b32_e32 v106, 4, v106
	v_lshl_add_u32 v110, v104, 9, v106
	v_add_u32_e32 v110, 0x24000, v110
	v_add_u32_e32 v106, 12, v105
	v_xor_b32_e32 v106, v106, v104
	v_lshlrev_b32_e32 v106, 4, v106
	v_lshl_add_u32 v111, v104, 9, v106
	v_add_u32_e32 v111, 0x24000, v111
	v_lshl_add_u64 v[120:121], v[116:117], 0, s[8:9]
	s_mov_b32 s13, 0x11600000
	v_add_co_u32_e32 v122, vcc, s13, v120
	s_mov_b32 s13, 0x11610000
	s_nop 0
	v_addc_co_u32_e32 v123, vcc, 0, v121, vcc
	global_load_dwordx4 v[124:127], v[122:123], off
	v_add_co_u32_e32 v120, vcc, s13, v120
	s_nop 1
	v_addc_co_u32_e32 v121, vcc, 0, v121, vcc
	global_load_dwordx4 v[128:131], v[120:121], off
.Lcr_loop:
	v_mov_b32_e32 v164, v162
	s_waitcnt vmcnt(0)
	ds_write_b128 v103, v[124:127]
	ds_write_b128 v103, v[128:131] offset:8192
	s_add_u32 s8, s8, 0x20000
	s_addc_u32 s9, s9, 0
	v_lshl_add_u64 v[120:121], v[116:117], 0, s[8:9]
	s_mov_b32 s13, 0x11600000
	v_add_co_u32_e32 v122, vcc, s13, v120
	s_mov_b32 s13, 0x11610000
	s_nop 0
	v_addc_co_u32_e32 v123, vcc, 0, v121, vcc
	global_load_dwordx4 v[124:127], v[122:123], off
	v_add_co_u32_e32 v120, vcc, s13, v120
	s_nop 1
	v_addc_co_u32_e32 v121, vcc, 0, v121, vcc
	global_load_dwordx4 v[128:131], v[120:121], off
	s_waitcnt lgkmcnt(0)
	s_barrier
	ds_read_b128 v[166:169], v108
	ds_read_b128 v[170:173], v109
	ds_read_b128 v[190:193], v110
	ds_read_b128 v[194:197], v111
	ds_read_b128 v[198:201], v108 offset:256
	ds_read_b128 v[202:205], v109 offset:256
	ds_read_b128 v[206:209], v110 offset:256
	ds_read_b128 v[210:213], v111 offset:256
	ds_read_b128 v[214:217], v108 offset:8192
	ds_read_b128 v[218:221], v109 offset:8192
	ds_read_b128 v[222:225], v110 offset:8192
	ds_read_b128 v[226:229], v111 offset:8192
	ds_read_b128 v[230:233], v108 offset:8448
	ds_read_b128 v[234:237], v109 offset:8448
	ds_read_b128 v[238:241], v110 offset:8448
	ds_read_b128 v[242:245], v111 offset:8448
	s_waitcnt lgkmcnt(0)
	s_barrier
; __device__ __forceinline__ unsigned pk2(float lo, float hi) { return f2bf(lo) | (f2bf(hi) << 16); }
; __device__ __forceinline__ void cross_phase(const Ctx& C, const bf16* Q, const bf16* KV  , bf16* O) {
;     ...
;                 for (int kt = 0; kt < 2; ++kt) { st[kt] = (f32x4){0.f, 0.f, 0.f, 0.f};
; #pragma unroll
;                     for (int ks = 0; ks < KS; ++ks) st[kt] = __builtin_amdgcn_mfma_f32_16x16x32_bf16(kf[kt][ks], qf[ks], st[kt], 0, 0, 0); }
;                 float pv[8];
; #pragma unroll
;                 for (int kt = 0; kt < 2; ++kt)
; #pragma unroll
;                     for (int j = 0; j < 4; ++j) pv[kt * 4 + j] = st[kt][j] * (0.0625f * LOG2E);
;                 float cm = pv[0];
; #pragma unroll
;                 for (int r = 1; r < 8; ++r) cm = fmaxf(cm, pv[r]);
;                 cm = fmaxf(cm, __shfl_xor(cm, 16)); cm = fmaxf(cm, __shfl_xor(cm, 32));
;                 const float mn = fmaxf(m_run, cm), sc = exp2f(m_run - mn);
;                 float ls = 0.f;
; #pragma unroll
;                 for (int r = 0; r < 8; ++r) { pv[r] = exp2f(pv[r] - mn); ls += pv[r]; }
;                 ls += __shfl_xor(ls, 16); ls += __shfl_xor(ls, 32);
;                 l_run = l_run * sc + ls; m_run = mn;
; #pragma unroll
;                 for (int dt = 0; dt < DT; ++dt) oacc[dt] = oacc[dt] * sc;
;                 bf16x8 pb; { v4u t; t.x = pk2(pv[0], pv[1]); t.y = pk2(pv[2], pv[3]); t.z = pk2(pv[4], pv[5]); t.w = pk2(pv[6], pv[7]); pb = __builtin_bit_cast(bf16x8, t); }
; #pragma unroll
;                 for (int d4 = 0; d4 < DT; d4 += 4) { bf16x8 vf4[4]; read_vfrags4_trp<P>(vs + (32 * c) * P + 16 * d4, i, g, vf4);
; #pragma unroll
;                     for (int dt = 0; dt < 4; ++dt) oacc[d4 + dt] = __builtin_amdgcn_mfma_f32_16x16x32_bf16(vf4[dt], pb, oacc[d4 + dt], 0, 0, 0); }
	v_mfma_f32_16x16x32_bf16 v[166:169], v[166:169], v[0:3], 0
	v_mfma_f32_16x16x32_bf16 v[166:169], v[170:173], v[4:7], v[166:169]
	v_mfma_f32_16x16x32_bf16 v[170:173], v[214:217], v[0:3], 0
	v_mfma_f32_16x16x32_bf16 v[170:173], v[218:221], v[4:7], v[170:173]
	v_mfma_f32_16x16x32_bf16 v[166:169], v[190:193], v[8:11], v[166:169]
	v_mfma_f32_16x16x32_bf16 v[170:173], v[222:225], v[8:11], v[170:173]
	v_mfma_f32_16x16x32_bf16 v[166:169], v[194:197], v[12:15], v[166:169]
	v_mfma_f32_16x16x32_bf16 v[170:173], v[226:229], v[12:15], v[170:173]
	v_mfma_f32_16x16x32_bf16 v[166:169], v[198:201], v[16:19], v[166:169]
	v_mfma_f32_16x16x32_bf16 v[170:173], v[230:233], v[16:19], v[170:173]
	v_mfma_f32_16x16x32_bf16 v[166:169], v[202:205], v[20:23], v[166:169]
	v_mfma_f32_16x16x32_bf16 v[170:173], v[234:237], v[20:23], v[170:173]
	v_mfma_f32_16x16x32_bf16 v[166:169], v[206:209], v[24:27], v[166:169]
	v_mfma_f32_16x16x32_bf16 v[170:173], v[238:241], v[24:27], v[170:173]
	v_mfma_f32_16x16x32_bf16 v[166:169], v[210:213], v[28:31], v[166:169]
	v_mfma_f32_16x16x32_bf16 v[170:173], v[242:245], v[28:31], v[170:173]
	s_cmp_lg_u32 s8, 0x100000
	s_nop 5
	v_mul_f32_e32 v73, 0x3db8aa3b, v166
	v_mul_f32_e32 v74, 0x3db8aa3b, v167
	v_mul_f32_e32 v75, 0x3db8aa3b, v168
	v_mul_f32_e32 v136, 0x3db8aa3b, v169
	v_max_f32_e32 v73, v73, v74
	v_mul_f32_e32 v162, 0x3db8aa3b, v170
	v_mul_f32_e32 v163, 0x3db8aa3b, v171
	v_max3_f32 v73, v73, v75, v136
	v_mul_f32_e32 v165, 0x3db8aa3b, v172
	v_mul_f32_e32 v174, 0x3db8aa3b, v173
	v_max3_f32 v73, v73, v162, v163
	v_max3_f32 v73, v73, v165, v174
	ds_bpermute_b32 v74, v159, v73
	v_add_u32_e32 v174, 0xfffffe80, v161
	s_waitcnt lgkmcnt(0)
	v_max_f32_e32 v74, v74, v74
	v_max_f32_e32 v73, v73, v74
	ds_bpermute_b32 v74, v160, v73
	s_waitcnt lgkmcnt(0)
	v_max3_f32 v163, v72, v73, v74
	v_fma_f32 v73, v166, s55, -v163
	v_fma_f32 v136, v168, s55, -v163
	v_sub_f32_e32 v72, v72, v163
	v_exp_f32_e32 v73, v73
	v_fma_f32 v74, v167, s55, -v163
	s_nop 1
	v_exp_f32_e32 v74, v74
	s_nop 0
	v_exp_f32_e32 v136, v136
	v_add_f32_e32 v75, v73, v74
	v_mov_b32_e32 v165, v136
	v_fma_f32 v136, v169, s55, -v163
	v_add_f32_e32 v75, v165, v75
	s_nop 0
	v_exp_f32_e32 v136, v136
	s_nop 0
	v_mov_b32_e32 v166, v136
	v_fma_f32 v136, v170, s55, -v163
	v_add_f32_e32 v75, v166, v75
	s_nop 0
	v_exp_f32_e32 v136, v136
	s_nop 0
	v_mov_b32_e32 v167, v136
	v_fma_f32 v136, v171, s55, -v163
	v_add_f32_e32 v75, v167, v75
	v_bfe_u32 v171, v166, 16, 1
	v_exp_f32_e32 v136, v136
	v_add3_u32 v166, v166, v171, s86
	v_mov_b32_e32 v168, v136
	v_fma_f32 v136, v172, s55, -v163
	v_add_f32_e32 v75, v168, v75
	v_bfe_u32 v172, v74, 16, 1
	v_exp_f32_e32 v136, v136
	v_add3_u32 v172, v74, v172, s86
	v_mov_b32_e32 v169, v136
	v_fma_f32 v136, v173, s55, -v163
	v_add_f32_e32 v75, v169, v75
	v_bfe_u32 v171, v169, 16, 1
	v_exp_f32_e32 v136, v136
	v_add3_u32 v169, v169, v171, s86
	v_mov_b32_e32 v170, v136
	v_exp_f32_e32 v72, v72
	v_add_f32_e32 v75, v170, v75
	v_mov_b32_e32 v136, v72
	ds_bpermute_b32 v72, v159, v75
	v_pk_mul_f32 v[98:99], v[98:99], v[136:137] op_sel_hi:[1,0]
	v_pk_mul_f32 v[96:97], v[96:97], v[136:137] op_sel_hi:[1,0]
	v_pk_mul_f32 v[78:79], v[78:79], v[136:137] op_sel_hi:[1,0]
	v_pk_mul_f32 v[76:77], v[76:77], v[136:137] op_sel_hi:[1,0]
	s_waitcnt lgkmcnt(0)
	v_add_f32_e32 v72, v75, v72
	ds_bpermute_b32 v75, v160, v72
	v_pk_mul_f32 v[70:71], v[70:71], v[136:137] op_sel_hi:[1,0]
	v_pk_mul_f32 v[68:69], v[68:69], v[136:137] op_sel_hi:[1,0]
	v_pk_mul_f32 v[46:47], v[46:47], v[136:137] op_sel_hi:[1,0]
	v_pk_mul_f32 v[44:45], v[44:45], v[136:137] op_sel_hi:[1,0]
	s_waitcnt lgkmcnt(0)
	v_add_f32_e32 v162, v72, v75
	v_bfe_u32 v72, v170, 16, 1
	v_bfe_u32 v75, v168, 16, 1
	v_add3_u32 v74, v168, v75, s86
	v_add3_u32 v72, v170, v72, s86
	v_bfe_u32 v75, v73, 16, 1
	v_bfe_u32 v168, v165, 16, 1
	v_bfe_u32 v170, v167, 16, 1
	v_add3_u32 v167, v167, v170, s86
	v_add3_u32 v165, v165, v168, s86
	v_add3_u32 v73, v73, v75, s86
	v_lshrrev_b32_e32 v168, 16, v73
	v_lshrrev_b32_e32 v73, 16, v165
	v_lshrrev_b32_e32 v165, 16, v167
	v_lshrrev_b32_e32 v75, 16, v169
	v_and_or_b32 v75, v72, s85, v75
	v_and_or_b32 v74, v74, s85, v165
	v_and_or_b32 v73, v166, s85, v73
	v_and_or_b32 v72, v172, s85, v168
	v_add_u32_e32 v165, 0xffffdd80, v161
	ds_read_b64_tr_b16 v[194:195], v165
	ds_read_b64_tr_b16 v[190:191], v165 offset:32
	ds_read_b64_tr_b16 v[170:171], v165 offset:64
	ds_read_b64_tr_b16 v[166:167], v165 offset:96
	ds_read_b64_tr_b16 v[196:197], v174
	ds_read_b64_tr_b16 v[192:193], v174 offset:32
	ds_read_b64_tr_b16 v[172:173], v174 offset:64
	ds_read_b64_tr_b16 v[168:169], v174 offset:96
	s_waitcnt lgkmcnt(0)
	v_pk_mul_f32 v[50:51], v[50:51], v[136:137] op_sel_hi:[1,0]
	v_pk_mul_f32 v[48:49], v[48:49], v[136:137] op_sel_hi:[1,0]
	v_pk_mul_f32 v[42:43], v[42:43], v[136:137] op_sel_hi:[1,0]
	v_pk_mul_f32 v[40:41], v[40:41], v[136:137] op_sel_hi:[1,0]
	v_pk_mul_f32 v[38:39], v[38:39], v[136:137] op_sel_hi:[1,0]
	v_pk_mul_f32 v[36:37], v[36:37], v[136:137] op_sel_hi:[1,0]
	v_pk_mul_f32 v[34:35], v[34:35], v[136:137] op_sel_hi:[1,0]
	v_pk_mul_f32 v[32:33], v[32:33], v[136:137] op_sel_hi:[1,0]
	v_mfma_f32_16x16x32_bf16 v[96:99], v[194:197], v[72:75], v[96:99]
	v_add_u32_e32 v165, 0xffffde00, v161
	v_add_u32_e32 v174, 0xffffff00, v161
	v_pk_mul_f32 v[82:83], v[82:83], v[136:137] op_sel_hi:[1,0]
	v_mfma_f32_16x16x32_bf16 v[76:79], v[190:193], v[72:75], v[76:79]
	v_mul_f32_e64 v80, v80, v136
	v_mul_f32_e64 v81, v81, v136
	v_pk_mul_f32 v[86:87], v[86:87], v[136:137] op_sel_hi:[1,0]
	v_pk_mul_f32 v[84:85], v[84:85], v[136:137] op_sel_hi:[1,0]
	v_mfma_f32_16x16x32_bf16 v[68:71], v[170:173], v[72:75], v[68:71]
	v_mul_f32_e64 v90, v90, v136
	v_mul_f32_e64 v91, v91, v136
	v_pk_mul_f32 v[88:89], v[88:89], v[136:137] op_sel_hi:[1,0]
	v_pk_mul_f32 v[94:95], v[94:95], v[136:137] op_sel_hi:[1,0]
	v_mfma_f32_16x16x32_bf16 v[44:47], v[166:169], v[72:75], v[44:47]
	ds_read_b64_tr_b16 v[194:195], v165
	ds_read_b64_tr_b16 v[190:191], v165 offset:32
	ds_read_b64_tr_b16 v[170:171], v165 offset:64
	ds_read_b64_tr_b16 v[166:167], v165 offset:96
	ds_read_b64_tr_b16 v[196:197], v174
	ds_read_b64_tr_b16 v[192:193], v174 offset:32
	ds_read_b64_tr_b16 v[172:173], v174 offset:64
	ds_read_b64_tr_b16 v[168:169], v174 offset:96
	s_waitcnt lgkmcnt(0)
; __device__ __forceinline__ unsigned pk2(float lo, float hi) { return f2bf(lo) | (f2bf(hi) << 16); }
; __device__ __forceinline__ void cross_phase(const Ctx& C, const bf16* Q, const bf16* KV  , bf16* O) {
;     ...
;                 for (int dt = 0; dt < DT; ++dt) oacc[dt] = oacc[dt] * sc;
;                 bf16x8 pb; { v4u t; t.x = pk2(pv[0], pv[1]); t.y = pk2(pv[2], pv[3]); t.z = pk2(pv[4], pv[5]); t.w = pk2(pv[6], pv[7]); pb = __builtin_bit_cast(bf16x8, t); }
; #pragma unroll
;                 for (int d4 = 0; d4 < DT; d4 += 4) { bf16x8 vf4[4]; read_vfrags4_trp<P>(vs + (32 * c) * P + 16 * d4, i, g, vf4);
; #pragma unroll
;                     for (int dt = 0; dt < 4; ++dt) oacc[d4 + dt] = __builtin_amdgcn_mfma_f32_16x16x32_bf16(vf4[dt], pb, oacc[d4 + dt], 0, 0, 0); }
;             }
;     ...
;             const float il = 1.0f / l_run;
;             bf16* op = O + (size_t)(b * SEQ + t0 + i) * DM + hd * 256 + 4 * g;
; #pragma unroll
;             for (int dt = 0; dt < DT; ++dt) { v2u w; w.x = pk2(oacc[dt].x * il, oacc[dt].y * il); w.y = pk2(oacc[dt].z * il, oacc[dt].w * il); *(v2u*)(op + 16 * dt) = w; }
	v_mul_f32_e64 v92, v92, v136
	v_mul_f32_e64 v93, v93, v136
	v_pk_mul_f32 v[54:55], v[54:55], v[136:137] op_sel_hi:[1,0]
	v_pk_mul_f32 v[52:53], v[52:53], v[136:137] op_sel_hi:[1,0]
	v_pk_mul_f32 v[58:59], v[58:59], v[136:137] op_sel_hi:[1,0]
	v_pk_mul_f32 v[56:57], v[56:57], v[136:137] op_sel_hi:[1,0]
	v_pk_mul_f32 v[62:63], v[62:63], v[136:137] op_sel_hi:[1,0]
	v_pk_mul_f32 v[60:61], v[60:61], v[136:137] op_sel_hi:[1,0]
	v_pk_mul_f32 v[66:67], v[66:67], v[136:137] op_sel_hi:[1,0]
	v_pk_mul_f32 v[64:65], v[64:65], v[136:137] op_sel_hi:[1,0]
	v_mfma_f32_16x16x32_bf16 v[48:51], v[194:197], v[72:75], v[48:51]
	v_add_u32_e32 v165, 0xffffde80, v161
	v_add_u32_e32 v174, 0xffffff80, v161
	v_fmac_f32_e32 v162, v164, v136
	v_mfma_f32_16x16x32_bf16 v[40:43], v[190:193], v[72:75], v[40:43]
	v_mfma_f32_16x16x32_bf16 v[36:39], v[170:173], v[72:75], v[36:39]
	v_mfma_f32_16x16x32_bf16 v[32:35], v[166:169], v[72:75], v[32:35]
	ds_read_b64_tr_b16 v[194:195], v165
	ds_read_b64_tr_b16 v[190:191], v165 offset:32
	ds_read_b64_tr_b16 v[170:171], v165 offset:64
	ds_read_b64_tr_b16 v[166:167], v165 offset:96
	ds_read_b64_tr_b16 v[196:197], v174
	ds_read_b64_tr_b16 v[192:193], v174 offset:32
	ds_read_b64_tr_b16 v[172:173], v174 offset:64
	ds_read_b64_tr_b16 v[168:169], v174 offset:96
	s_waitcnt lgkmcnt(0)
	v_add_u32_e32 v165, 0xffffdf00, v161
	v_mfma_f32_16x16x32_bf16 v[80:83], v[194:197], v[72:75], v[80:83]
	v_mfma_f32_16x16x32_bf16 v[84:87], v[190:193], v[72:75], v[84:87]
	v_mfma_f32_16x16x32_bf16 v[88:91], v[170:173], v[72:75], v[88:91]
	v_mfma_f32_16x16x32_bf16 v[92:95], v[166:169], v[72:75], v[92:95]
	ds_read_b64_tr_b16 v[194:195], v165
	ds_read_b64_tr_b16 v[190:191], v165 offset:32
	ds_read_b64_tr_b16 v[170:171], v165 offset:64
	ds_read_b64_tr_b16 v[166:167], v165 offset:96
	ds_read_b64_tr_b16 v[196:197], v161
	ds_read_b64_tr_b16 v[192:193], v161 offset:32
	ds_read_b64_tr_b16 v[172:173], v161 offset:64
	ds_read_b64_tr_b16 v[168:169], v161 offset:96
	s_waitcnt lgkmcnt(0)
	v_add_u32_e32 v161, 0x4200, v161
	v_mfma_f32_16x16x32_bf16 v[52:55], v[194:197], v[72:75], v[52:55]
	v_mfma_f32_16x16x32_bf16 v[56:59], v[190:193], v[72:75], v[56:59]
	v_mfma_f32_16x16x32_bf16 v[60:63], v[170:173], v[72:75], v[60:63]
	v_mfma_f32_16x16x32_bf16 v[64:67], v[166:169], v[72:75], v[64:67]
	v_mov_b32_e32 v72, v163
	s_cbranch_scc1 .Lcr_loop
	s_waitcnt vmcnt(0)
.Lcr_after:
	v_div_scale_f32 v1, s[8:9], v162, v162, 1.0
	v_rcp_f32_e32 v2, v1
	v_lshlrev_b32_e32 v0, 2, v133
	s_add_i32 s12, s12, 1
	s_cmp_eq_u32 s12, 8
	v_fma_f32 v3, -v1, v2, 1.0
	v_fmac_f32_e32 v2, v3, v2
	v_div_scale_f32 v3, vcc, 1.0, v162, 1.0
	v_mul_f32_e32 v4, v3, v2
	v_fma_f32 v5, -v1, v4, v3
	v_fmac_f32_e32 v4, v5, v2
	v_fma_f32 v1, -v1, v4, v3
	v_div_fmas_f32 v1, v1, v2, v4
	v_div_fixup_f32 v2, v1, v162, 1.0
	v_lshl_add_u64 v[4:5], v[134:135], 1, s[4:5]
	v_ashrrev_i32_e32 v1, 31, v0
	v_lshl_add_u64 v[0:1], v[0:1], 1, v[4:5]
	v_mov_b32_e32 v4, v96
	v_mov_b32_e32 v5, v98
	v_pk_mul_f32 v[4:5], v[4:5], v[2:3] op_sel_hi:[1,0]
	v_mov_b32_e32 v98, v97
	v_pk_mul_f32 v[6:7], v[98:99], v[2:3] op_sel_hi:[1,0]
	v_and_b32_sdwa v3, v5, v182 dst_sel:DWORD dst_unused:UNUSED_PAD src0_sel:WORD_1 src1_sel:DWORD
	v_and_b32_sdwa v8, v4, v182 dst_sel:DWORD dst_unused:UNUSED_PAD src0_sel:WORD_1 src1_sel:DWORD
	v_add3_u32 v4, v4, v8, s86
	v_add3_u32 v3, v5, v3, s86
	v_and_b32_sdwa v5, v7, v182 dst_sel:DWORD dst_unused:UNUSED_PAD src0_sel:WORD_1 src1_sel:DWORD
	v_and_b32_sdwa v8, v6, v182 dst_sel:DWORD dst_unused:UNUSED_PAD src0_sel:WORD_1 src1_sel:DWORD
	v_add3_u32 v5, v7, v5, s86
	v_add3_u32 v6, v6, v8, s86
	v_and_b32_e32 v5, 0xffff0000, v5
	v_and_b32_e32 v6, 0xffff0000, v6
	v_or_b32_sdwa v5, v5, v3 dst_sel:DWORD dst_unused:UNUSED_PAD src0_sel:DWORD src1_sel:WORD_1
	v_or_b32_sdwa v4, v6, v4 dst_sel:DWORD dst_unused:UNUSED_PAD src0_sel:DWORD src1_sel:WORD_1
	global_store_dwordx2 v[0:1], v[4:5], off
	v_mov_b32_e32 v4, v76
	v_mov_b32_e32 v5, v78
	v_pk_mul_f32 v[4:5], v[4:5], v[2:3] op_sel_hi:[1,0]
	v_mov_b32_e32 v78, v77
	v_pk_mul_f32 v[6:7], v[78:79], v[2:3] op_sel_hi:[1,0]
	v_and_b32_sdwa v3, v5, v182 dst_sel:DWORD dst_unused:UNUSED_PAD src0_sel:WORD_1 src1_sel:DWORD
	v_and_b32_sdwa v8, v4, v182 dst_sel:DWORD dst_unused:UNUSED_PAD src0_sel:WORD_1 src1_sel:DWORD
	v_add3_u32 v4, v4, v8, s86
	v_add3_u32 v3, v5, v3, s86
	v_and_b32_sdwa v5, v7, v182 dst_sel:DWORD dst_unused:UNUSED_PAD src0_sel:WORD_1 src1_sel:DWORD
	v_and_b32_sdwa v8, v6, v182 dst_sel:DWORD dst_unused:UNUSED_PAD src0_sel:WORD_1 src1_sel:DWORD
	v_add3_u32 v5, v7, v5, s86
	v_add3_u32 v6, v6, v8, s86
	v_and_b32_e32 v5, 0xffff0000, v5
	v_and_b32_e32 v6, 0xffff0000, v6
	v_or_b32_sdwa v5, v5, v3 dst_sel:DWORD dst_unused:UNUSED_PAD src0_sel:DWORD src1_sel:WORD_1
	v_or_b32_sdwa v4, v6, v4 dst_sel:DWORD dst_unused:UNUSED_PAD src0_sel:DWORD src1_sel:WORD_1
	global_store_dwordx2 v[0:1], v[4:5], off offset:32
	v_mov_b32_e32 v4, v68
	v_mov_b32_e32 v5, v70
	v_pk_mul_f32 v[4:5], v[4:5], v[2:3] op_sel_hi:[1,0]
	v_mov_b32_e32 v70, v69
	v_pk_mul_f32 v[6:7], v[70:71], v[2:3] op_sel_hi:[1,0]
	v_and_b32_sdwa v3, v5, v182 dst_sel:DWORD dst_unused:UNUSED_PAD src0_sel:WORD_1 src1_sel:DWORD
	v_and_b32_sdwa v8, v4, v182 dst_sel:DWORD dst_unused:UNUSED_PAD src0_sel:WORD_1 src1_sel:DWORD
	v_add3_u32 v4, v4, v8, s86
	v_add3_u32 v3, v5, v3, s86
	v_and_b32_sdwa v5, v7, v182 dst_sel:DWORD dst_unused:UNUSED_PAD src0_sel:WORD_1 src1_sel:DWORD
	v_and_b32_sdwa v8, v6, v182 dst_sel:DWORD dst_unused:UNUSED_PAD src0_sel:WORD_1 src1_sel:DWORD
	v_add3_u32 v5, v7, v5, s86
	v_add3_u32 v6, v6, v8, s86
	v_and_b32_e32 v5, 0xffff0000, v5
	v_and_b32_e32 v6, 0xffff0000, v6
	v_or_b32_sdwa v5, v5, v3 dst_sel:DWORD dst_unused:UNUSED_PAD src0_sel:DWORD src1_sel:WORD_1
; __device__ __forceinline__ unsigned pk2(float lo, float hi) { return f2bf(lo) | (f2bf(hi) << 16); }
; __device__ __forceinline__ void cross_phase(const Ctx& C, const bf16* Q, const bf16* KV  , bf16* O) {
;     ...
;             const float il = 1.0f / l_run;
;             bf16* op = O + (size_t)(b * SEQ + t0 + i) * DM + hd * 256 + 4 * g;
; #pragma unroll
;             for (int dt = 0; dt < DT; ++dt) { v2u w; w.x = pk2(oacc[dt].x * il, oacc[dt].y * il); w.y = pk2(oacc[dt].z * il, oacc[dt].w * il); *(v2u*)(op + 16 * dt) = w; }
	v_or_b32_sdwa v4, v6, v4 dst_sel:DWORD dst_unused:UNUSED_PAD src0_sel:DWORD src1_sel:WORD_1
	global_store_dwordx2 v[0:1], v[4:5], off offset:64
	v_mov_b32_e32 v4, v44
	v_mov_b32_e32 v5, v46
	v_pk_mul_f32 v[4:5], v[4:5], v[2:3] op_sel_hi:[1,0]
	v_mov_b32_e32 v46, v45
	v_pk_mul_f32 v[6:7], v[46:47], v[2:3] op_sel_hi:[1,0]
	v_and_b32_sdwa v3, v5, v182 dst_sel:DWORD dst_unused:UNUSED_PAD src0_sel:WORD_1 src1_sel:DWORD
	v_and_b32_sdwa v8, v4, v182 dst_sel:DWORD dst_unused:UNUSED_PAD src0_sel:WORD_1 src1_sel:DWORD
	v_add3_u32 v4, v4, v8, s86
	v_add3_u32 v3, v5, v3, s86
	v_and_b32_sdwa v5, v7, v182 dst_sel:DWORD dst_unused:UNUSED_PAD src0_sel:WORD_1 src1_sel:DWORD
	v_and_b32_sdwa v8, v6, v182 dst_sel:DWORD dst_unused:UNUSED_PAD src0_sel:WORD_1 src1_sel:DWORD
	v_add3_u32 v5, v7, v5, s86
	v_add3_u32 v6, v6, v8, s86
	v_and_b32_e32 v5, 0xffff0000, v5
	v_and_b32_e32 v6, 0xffff0000, v6
	v_or_b32_sdwa v5, v5, v3 dst_sel:DWORD dst_unused:UNUSED_PAD src0_sel:DWORD src1_sel:WORD_1
	v_or_b32_sdwa v4, v6, v4 dst_sel:DWORD dst_unused:UNUSED_PAD src0_sel:DWORD src1_sel:WORD_1
	global_store_dwordx2 v[0:1], v[4:5], off offset:96
	v_mov_b32_e32 v4, v48
	v_mov_b32_e32 v5, v50
	v_pk_mul_f32 v[4:5], v[4:5], v[2:3] op_sel_hi:[1,0]
	v_mov_b32_e32 v50, v49
	v_pk_mul_f32 v[6:7], v[50:51], v[2:3] op_sel_hi:[1,0]
	v_and_b32_sdwa v3, v5, v182 dst_sel:DWORD dst_unused:UNUSED_PAD src0_sel:WORD_1 src1_sel:DWORD
	v_and_b32_sdwa v8, v4, v182 dst_sel:DWORD dst_unused:UNUSED_PAD src0_sel:WORD_1 src1_sel:DWORD
	v_add3_u32 v4, v4, v8, s86
	v_add3_u32 v3, v5, v3, s86
	v_and_b32_sdwa v5, v7, v182 dst_sel:DWORD dst_unused:UNUSED_PAD src0_sel:WORD_1 src1_sel:DWORD
	v_and_b32_sdwa v8, v6, v182 dst_sel:DWORD dst_unused:UNUSED_PAD src0_sel:WORD_1 src1_sel:DWORD
	v_add3_u32 v5, v7, v5, s86
	v_add3_u32 v6, v6, v8, s86
	v_and_b32_e32 v5, 0xffff0000, v5
	v_and_b32_e32 v6, 0xffff0000, v6
	v_or_b32_sdwa v5, v5, v3 dst_sel:DWORD dst_unused:UNUSED_PAD src0_sel:DWORD src1_sel:WORD_1
	v_or_b32_sdwa v4, v6, v4 dst_sel:DWORD dst_unused:UNUSED_PAD src0_sel:DWORD src1_sel:WORD_1
	global_store_dwordx2 v[0:1], v[4:5], off offset:128
	v_mov_b32_e32 v4, v40
	v_mov_b32_e32 v5, v42
	v_pk_mul_f32 v[4:5], v[4:5], v[2:3] op_sel_hi:[1,0]
	v_mov_b32_e32 v42, v41
	v_pk_mul_f32 v[6:7], v[42:43], v[2:3] op_sel_hi:[1,0]
	v_and_b32_sdwa v3, v5, v182 dst_sel:DWORD dst_unused:UNUSED_PAD src0_sel:WORD_1 src1_sel:DWORD
	v_and_b32_sdwa v8, v4, v182 dst_sel:DWORD dst_unused:UNUSED_PAD src0_sel:WORD_1 src1_sel:DWORD
	v_add3_u32 v4, v4, v8, s86
	v_add3_u32 v3, v5, v3, s86
	v_and_b32_sdwa v5, v7, v182 dst_sel:DWORD dst_unused:UNUSED_PAD src0_sel:WORD_1 src1_sel:DWORD
	v_and_b32_sdwa v8, v6, v182 dst_sel:DWORD dst_unused:UNUSED_PAD src0_sel:WORD_1 src1_sel:DWORD
	v_add3_u32 v5, v7, v5, s86
	v_add3_u32 v6, v6, v8, s86
	v_and_b32_e32 v5, 0xffff0000, v5
	v_and_b32_e32 v6, 0xffff0000, v6
	v_or_b32_sdwa v5, v5, v3 dst_sel:DWORD dst_unused:UNUSED_PAD src0_sel:DWORD src1_sel:WORD_1
	v_or_b32_sdwa v4, v6, v4 dst_sel:DWORD dst_unused:UNUSED_PAD src0_sel:DWORD src1_sel:WORD_1
	global_store_dwordx2 v[0:1], v[4:5], off offset:160
	v_mov_b32_e32 v4, v36
	v_mov_b32_e32 v5, v38
	v_pk_mul_f32 v[4:5], v[4:5], v[2:3] op_sel_hi:[1,0]
	v_mov_b32_e32 v38, v37
	v_pk_mul_f32 v[6:7], v[38:39], v[2:3] op_sel_hi:[1,0]
	v_and_b32_sdwa v3, v5, v182 dst_sel:DWORD dst_unused:UNUSED_PAD src0_sel:WORD_1 src1_sel:DWORD
	v_and_b32_sdwa v8, v4, v182 dst_sel:DWORD dst_unused:UNUSED_PAD src0_sel:WORD_1 src1_sel:DWORD
	v_add3_u32 v4, v4, v8, s86
	v_add3_u32 v3, v5, v3, s86
	v_and_b32_sdwa v5, v7, v182 dst_sel:DWORD dst_unused:UNUSED_PAD src0_sel:WORD_1 src1_sel:DWORD
	v_and_b32_sdwa v8, v6, v182 dst_sel:DWORD dst_unused:UNUSED_PAD src0_sel:WORD_1 src1_sel:DWORD
	v_add3_u32 v5, v7, v5, s86
	v_add3_u32 v6, v6, v8, s86
	v_and_b32_e32 v5, 0xffff0000, v5
	v_and_b32_e32 v6, 0xffff0000, v6
	v_or_b32_sdwa v5, v5, v3 dst_sel:DWORD dst_unused:UNUSED_PAD src0_sel:DWORD src1_sel:WORD_1
	v_or_b32_sdwa v4, v6, v4 dst_sel:DWORD dst_unused:UNUSED_PAD src0_sel:DWORD src1_sel:WORD_1
	global_store_dwordx2 v[0:1], v[4:5], off offset:192
	v_mov_b32_e32 v4, v32
	v_mov_b32_e32 v5, v34
	v_pk_mul_f32 v[4:5], v[4:5], v[2:3] op_sel_hi:[1,0]
	v_mov_b32_e32 v34, v33
	v_pk_mul_f32 v[6:7], v[34:35], v[2:3] op_sel_hi:[1,0]
	v_and_b32_sdwa v3, v5, v182 dst_sel:DWORD dst_unused:UNUSED_PAD src0_sel:WORD_1 src1_sel:DWORD
	v_and_b32_sdwa v8, v4, v182 dst_sel:DWORD dst_unused:UNUSED_PAD src0_sel:WORD_1 src1_sel:DWORD
	v_add3_u32 v4, v4, v8, s86
	v_add3_u32 v3, v5, v3, s86
	v_and_b32_sdwa v5, v7, v182 dst_sel:DWORD dst_unused:UNUSED_PAD src0_sel:WORD_1 src1_sel:DWORD
	v_and_b32_sdwa v8, v6, v182 dst_sel:DWORD dst_unused:UNUSED_PAD src0_sel:WORD_1 src1_sel:DWORD
	v_add3_u32 v5, v7, v5, s86
	v_add3_u32 v6, v6, v8, s86
	v_and_b32_e32 v5, 0xffff0000, v5
	v_and_b32_e32 v6, 0xffff0000, v6
	v_or_b32_sdwa v5, v5, v3 dst_sel:DWORD dst_unused:UNUSED_PAD src0_sel:DWORD src1_sel:WORD_1
	v_or_b32_sdwa v4, v6, v4 dst_sel:DWORD dst_unused:UNUSED_PAD src0_sel:DWORD src1_sel:WORD_1
	global_store_dwordx2 v[0:1], v[4:5], off offset:224
	v_mov_b32_e32 v4, v80
	v_mov_b32_e32 v5, v82
	v_pk_mul_f32 v[4:5], v[4:5], v[2:3] op_sel_hi:[1,0]
	v_mov_b32_e32 v82, v81
	v_pk_mul_f32 v[6:7], v[82:83], v[2:3] op_sel_hi:[1,0]
	v_and_b32_sdwa v3, v5, v182 dst_sel:DWORD dst_unused:UNUSED_PAD src0_sel:WORD_1 src1_sel:DWORD
	v_and_b32_sdwa v8, v4, v182 dst_sel:DWORD dst_unused:UNUSED_PAD src0_sel:WORD_1 src1_sel:DWORD
	v_add3_u32 v4, v4, v8, s86
	v_add3_u32 v3, v5, v3, s86
	v_and_b32_sdwa v5, v7, v182 dst_sel:DWORD dst_unused:UNUSED_PAD src0_sel:WORD_1 src1_sel:DWORD
	v_and_b32_sdwa v8, v6, v182 dst_sel:DWORD dst_unused:UNUSED_PAD src0_sel:WORD_1 src1_sel:DWORD
; __device__ __forceinline__ unsigned pk2(float lo, float hi) { return f2bf(lo) | (f2bf(hi) << 16); }
; __device__ __forceinline__ void cross_phase(const Ctx& C, const bf16* Q, const bf16* KV  , bf16* O) {
;     ...
;             const float il = 1.0f / l_run;
;             bf16* op = O + (size_t)(b * SEQ + t0 + i) * DM + hd * 256 + 4 * g;
; #pragma unroll
;             for (int dt = 0; dt < DT; ++dt) { v2u w; w.x = pk2(oacc[dt].x * il, oacc[dt].y * il); w.y = pk2(oacc[dt].z * il, oacc[dt].w * il); *(v2u*)(op + 16 * dt) = w; }
	v_add3_u32 v5, v7, v5, s86
	v_add3_u32 v6, v6, v8, s86
	v_and_b32_e32 v5, 0xffff0000, v5
	v_and_b32_e32 v6, 0xffff0000, v6
	v_or_b32_sdwa v5, v5, v3 dst_sel:DWORD dst_unused:UNUSED_PAD src0_sel:DWORD src1_sel:WORD_1
	v_or_b32_sdwa v4, v6, v4 dst_sel:DWORD dst_unused:UNUSED_PAD src0_sel:DWORD src1_sel:WORD_1
	global_store_dwordx2 v[0:1], v[4:5], off offset:256
	v_mov_b32_e32 v4, v84
	v_mov_b32_e32 v5, v86
	v_pk_mul_f32 v[4:5], v[4:5], v[2:3] op_sel_hi:[1,0]
	v_mov_b32_e32 v86, v85
	v_pk_mul_f32 v[6:7], v[86:87], v[2:3] op_sel_hi:[1,0]
	v_and_b32_sdwa v3, v5, v182 dst_sel:DWORD dst_unused:UNUSED_PAD src0_sel:WORD_1 src1_sel:DWORD
	v_and_b32_sdwa v8, v4, v182 dst_sel:DWORD dst_unused:UNUSED_PAD src0_sel:WORD_1 src1_sel:DWORD
	v_add3_u32 v4, v4, v8, s86
	v_add3_u32 v3, v5, v3, s86
	v_and_b32_sdwa v5, v7, v182 dst_sel:DWORD dst_unused:UNUSED_PAD src0_sel:WORD_1 src1_sel:DWORD
	v_and_b32_sdwa v8, v6, v182 dst_sel:DWORD dst_unused:UNUSED_PAD src0_sel:WORD_1 src1_sel:DWORD
	v_add3_u32 v5, v7, v5, s86
	v_add3_u32 v6, v6, v8, s86
	v_and_b32_e32 v5, 0xffff0000, v5
	v_and_b32_e32 v6, 0xffff0000, v6
	v_or_b32_sdwa v5, v5, v3 dst_sel:DWORD dst_unused:UNUSED_PAD src0_sel:DWORD src1_sel:WORD_1
	v_or_b32_sdwa v4, v6, v4 dst_sel:DWORD dst_unused:UNUSED_PAD src0_sel:DWORD src1_sel:WORD_1
	global_store_dwordx2 v[0:1], v[4:5], off offset:288
	v_mov_b32_e32 v4, v88
	v_mov_b32_e32 v5, v90
	v_pk_mul_f32 v[4:5], v[4:5], v[2:3] op_sel_hi:[1,0]
	v_mov_b32_e32 v90, v89
	v_pk_mul_f32 v[6:7], v[90:91], v[2:3] op_sel_hi:[1,0]
	v_and_b32_sdwa v3, v5, v182 dst_sel:DWORD dst_unused:UNUSED_PAD src0_sel:WORD_1 src1_sel:DWORD
	v_and_b32_sdwa v8, v4, v182 dst_sel:DWORD dst_unused:UNUSED_PAD src0_sel:WORD_1 src1_sel:DWORD
	v_add3_u32 v4, v4, v8, s86
	v_add3_u32 v3, v5, v3, s86
	v_and_b32_sdwa v5, v7, v182 dst_sel:DWORD dst_unused:UNUSED_PAD src0_sel:WORD_1 src1_sel:DWORD
	v_and_b32_sdwa v8, v6, v182 dst_sel:DWORD dst_unused:UNUSED_PAD src0_sel:WORD_1 src1_sel:DWORD
	v_add3_u32 v5, v7, v5, s86
	v_add3_u32 v6, v6, v8, s86
	v_and_b32_e32 v5, 0xffff0000, v5
	v_and_b32_e32 v6, 0xffff0000, v6
	v_or_b32_sdwa v5, v5, v3 dst_sel:DWORD dst_unused:UNUSED_PAD src0_sel:DWORD src1_sel:WORD_1
	v_or_b32_sdwa v4, v6, v4 dst_sel:DWORD dst_unused:UNUSED_PAD src0_sel:DWORD src1_sel:WORD_1
	global_store_dwordx2 v[0:1], v[4:5], off offset:320
	v_mov_b32_e32 v4, v92
	v_mov_b32_e32 v5, v94
	v_pk_mul_f32 v[4:5], v[4:5], v[2:3] op_sel_hi:[1,0]
	v_mov_b32_e32 v94, v93
	v_pk_mul_f32 v[6:7], v[94:95], v[2:3] op_sel_hi:[1,0]
	v_and_b32_sdwa v3, v5, v182 dst_sel:DWORD dst_unused:UNUSED_PAD src0_sel:WORD_1 src1_sel:DWORD
	v_and_b32_sdwa v8, v4, v182 dst_sel:DWORD dst_unused:UNUSED_PAD src0_sel:WORD_1 src1_sel:DWORD
	v_add3_u32 v4, v4, v8, s86
	v_add3_u32 v3, v5, v3, s86
	v_and_b32_sdwa v5, v7, v182 dst_sel:DWORD dst_unused:UNUSED_PAD src0_sel:WORD_1 src1_sel:DWORD
	v_and_b32_sdwa v8, v6, v182 dst_sel:DWORD dst_unused:UNUSED_PAD src0_sel:WORD_1 src1_sel:DWORD
	v_add3_u32 v5, v7, v5, s86
	v_add3_u32 v6, v6, v8, s86
	v_and_b32_e32 v5, 0xffff0000, v5
	v_and_b32_e32 v6, 0xffff0000, v6
	v_or_b32_sdwa v5, v5, v3 dst_sel:DWORD dst_unused:UNUSED_PAD src0_sel:DWORD src1_sel:WORD_1
	v_or_b32_sdwa v4, v6, v4 dst_sel:DWORD dst_unused:UNUSED_PAD src0_sel:DWORD src1_sel:WORD_1
	global_store_dwordx2 v[0:1], v[4:5], off offset:352
	v_mov_b32_e32 v4, v52
	v_mov_b32_e32 v5, v54
	v_pk_mul_f32 v[4:5], v[4:5], v[2:3] op_sel_hi:[1,0]
	v_mov_b32_e32 v54, v53
	v_pk_mul_f32 v[6:7], v[54:55], v[2:3] op_sel_hi:[1,0]
	v_and_b32_sdwa v3, v5, v182 dst_sel:DWORD dst_unused:UNUSED_PAD src0_sel:WORD_1 src1_sel:DWORD
	v_and_b32_sdwa v8, v4, v182 dst_sel:DWORD dst_unused:UNUSED_PAD src0_sel:WORD_1 src1_sel:DWORD
; __device__ __forceinline__ unsigned pk2(float lo, float hi) { return f2bf(lo) | (f2bf(hi) << 16); }
; __device__ __forceinline__ void cross_phase(const Ctx& C, const bf16* Q, const bf16* KV  , bf16* O) {
;     ...
;             const float il = 1.0f / l_run;
;             bf16* op = O + (size_t)(b * SEQ + t0 + i) * DM + hd * 256 + 4 * g;
; #pragma unroll
;             for (int dt = 0; dt < DT; ++dt) { v2u w; w.x = pk2(oacc[dt].x * il, oacc[dt].y * il); w.y = pk2(oacc[dt].z * il, oacc[dt].w * il); *(v2u*)(op + 16 * dt) = w; }
;         }
;         __syncthreads();
	v_add3_u32 v4, v4, v8, s86
	v_add3_u32 v3, v5, v3, s86
	v_and_b32_sdwa v5, v7, v182 dst_sel:DWORD dst_unused:UNUSED_PAD src0_sel:WORD_1 src1_sel:DWORD
	v_and_b32_sdwa v8, v6, v182 dst_sel:DWORD dst_unused:UNUSED_PAD src0_sel:WORD_1 src1_sel:DWORD
	v_add3_u32 v5, v7, v5, s86
	v_add3_u32 v6, v6, v8, s86
	v_and_b32_e32 v5, 0xffff0000, v5
	v_and_b32_e32 v6, 0xffff0000, v6
	v_or_b32_sdwa v5, v5, v3 dst_sel:DWORD dst_unused:UNUSED_PAD src0_sel:DWORD src1_sel:WORD_1
	v_or_b32_sdwa v4, v6, v4 dst_sel:DWORD dst_unused:UNUSED_PAD src0_sel:DWORD src1_sel:WORD_1
	global_store_dwordx2 v[0:1], v[4:5], off offset:384
	v_mov_b32_e32 v4, v56
	v_mov_b32_e32 v5, v58
	v_pk_mul_f32 v[4:5], v[2:3], v[4:5] op_sel_hi:[0,1]
	v_mov_b32_e32 v58, v57
	v_pk_mul_f32 v[6:7], v[2:3], v[58:59] op_sel_hi:[0,1]
	v_and_b32_sdwa v3, v5, v182 dst_sel:DWORD dst_unused:UNUSED_PAD src0_sel:WORD_1 src1_sel:DWORD
	v_and_b32_sdwa v8, v4, v182 dst_sel:DWORD dst_unused:UNUSED_PAD src0_sel:WORD_1 src1_sel:DWORD
	v_add3_u32 v4, v4, v8, s86
	v_add3_u32 v3, v5, v3, s86
	v_and_b32_sdwa v5, v7, v182 dst_sel:DWORD dst_unused:UNUSED_PAD src0_sel:WORD_1 src1_sel:DWORD
	v_and_b32_sdwa v8, v6, v182 dst_sel:DWORD dst_unused:UNUSED_PAD src0_sel:WORD_1 src1_sel:DWORD
	v_add3_u32 v5, v7, v5, s86
	v_add3_u32 v6, v6, v8, s86
	v_and_b32_e32 v5, 0xffff0000, v5
	v_and_b32_e32 v6, 0xffff0000, v6
	v_or_b32_sdwa v5, v5, v3 dst_sel:DWORD dst_unused:UNUSED_PAD src0_sel:DWORD src1_sel:WORD_1
	v_or_b32_sdwa v4, v6, v4 dst_sel:DWORD dst_unused:UNUSED_PAD src0_sel:DWORD src1_sel:WORD_1
	global_store_dwordx2 v[0:1], v[4:5], off offset:416
	v_mov_b32_e32 v4, v60
	v_mov_b32_e32 v5, v62
	v_pk_mul_f32 v[4:5], v[2:3], v[4:5] op_sel_hi:[0,1]
	v_mov_b32_e32 v62, v61
	v_pk_mul_f32 v[6:7], v[2:3], v[62:63] op_sel_hi:[0,1]
	v_and_b32_sdwa v3, v5, v182 dst_sel:DWORD dst_unused:UNUSED_PAD src0_sel:WORD_1 src1_sel:DWORD
	v_and_b32_sdwa v8, v4, v182 dst_sel:DWORD dst_unused:UNUSED_PAD src0_sel:WORD_1 src1_sel:DWORD
	v_add3_u32 v4, v4, v8, s86
	v_add3_u32 v3, v5, v3, s86
	v_and_b32_sdwa v5, v7, v182 dst_sel:DWORD dst_unused:UNUSED_PAD src0_sel:WORD_1 src1_sel:DWORD
	v_and_b32_sdwa v8, v6, v182 dst_sel:DWORD dst_unused:UNUSED_PAD src0_sel:WORD_1 src1_sel:DWORD
	v_add3_u32 v5, v7, v5, s86
	v_add3_u32 v6, v6, v8, s86
	v_and_b32_e32 v5, 0xffff0000, v5
	v_and_b32_e32 v6, 0xffff0000, v6
	v_or_b32_sdwa v5, v5, v3 dst_sel:DWORD dst_unused:UNUSED_PAD src0_sel:DWORD src1_sel:WORD_1
	v_or_b32_sdwa v4, v6, v4 dst_sel:DWORD dst_unused:UNUSED_PAD src0_sel:DWORD src1_sel:WORD_1
	global_store_dwordx2 v[0:1], v[4:5], off offset:448
	v_mov_b32_e32 v4, v64
	v_mov_b32_e32 v5, v66
	v_pk_mul_f32 v[4:5], v[2:3], v[4:5] op_sel_hi:[0,1]
	v_mov_b32_e32 v66, v65
	v_pk_mul_f32 v[2:3], v[2:3], v[66:67] op_sel_hi:[0,1]
	v_and_b32_sdwa v6, v5, v182 dst_sel:DWORD dst_unused:UNUSED_PAD src0_sel:WORD_1 src1_sel:DWORD
	v_and_b32_sdwa v7, v4, v182 dst_sel:DWORD dst_unused:UNUSED_PAD src0_sel:WORD_1 src1_sel:DWORD
	v_add3_u32 v4, v4, v7, s86
	v_add3_u32 v5, v5, v6, s86
	v_and_b32_sdwa v6, v3, v182 dst_sel:DWORD dst_unused:UNUSED_PAD src0_sel:WORD_1 src1_sel:DWORD
	v_and_b32_sdwa v7, v2, v182 dst_sel:DWORD dst_unused:UNUSED_PAD src0_sel:WORD_1 src1_sel:DWORD
	v_add3_u32 v3, v3, v6, s86
	v_add3_u32 v2, v2, v7, s86
	v_and_b32_e32 v3, 0xffff0000, v3
	v_and_b32_e32 v2, 0xffff0000, v2
	v_or_b32_sdwa v3, v3, v5 dst_sel:DWORD dst_unused:UNUSED_PAD src0_sel:DWORD src1_sel:WORD_1
	v_or_b32_sdwa v2, v2, v4 dst_sel:DWORD dst_unused:UNUSED_PAD src0_sel:DWORD src1_sel:WORD_1
	global_store_dwordx2 v[0:1], v[2:3], off offset:480
	s_cbranch_scc0 .LBB0_292
	s_add_i32 s10, s10, s96
	s_add_i32 s2, s2, s83
	s_cmpk_gt_i32 s10, 0xff
	s_barrier
	s_cbranch_scc0 .LBB0_291

; #define LAS __attribute__((address_space(3)))
; __global__ void __launch_bounds__(512, 2) mk_fwd(Args a) {
;     extern __shared__ __attribute__((aligned(16))) unsigned char lds_raw[];
;     Ctx C; C.lds = (LAS unsigned char*)lds_raw; C.wave = __builtin_amdgcn_readfirstlane((int)threadIdx.x >> 6);
	.amdhsa_kernel _Z6mk_fwd4Args
		.amdhsa_group_segment_fixed_size 16384
		.amdhsa_private_segment_fixed_size 0
		.amdhsa_kernarg_size 432
		.amdhsa_user_sgpr_count 2
		.amdhsa_user_sgpr_dispatch_ptr 0
		.amdhsa_user_sgpr_queue_ptr 0
		.amdhsa_user_sgpr_kernarg_segment_ptr 1
		.amdhsa_user_sgpr_dispatch_id 0
		.amdhsa_user_sgpr_kernarg_preload_length 0
		.amdhsa_user_sgpr_kernarg_preload_offset 0
		.amdhsa_user_sgpr_private_segment_size 0
		.amdhsa_uses_dynamic_stack 0
		.amdhsa_enable_private_segment 0
		.amdhsa_system_sgpr_workgroup_id_x 1
		.amdhsa_system_sgpr_workgroup_id_y 0
		.amdhsa_system_sgpr_workgroup_id_z 0
		.amdhsa_system_sgpr_workgroup_info 0
		.amdhsa_system_vgpr_workitem_id 2
		.amdhsa_next_free_vgpr 250
		.amdhsa_next_free_sgpr 100
		.amdhsa_accum_offset 252
		.amdhsa_reserve_vcc 1
		.amdhsa_float_round_mode_32 0
		.amdhsa_float_round_mode_16_64 0
		.amdhsa_float_denorm_mode_32 3
		.amdhsa_float_denorm_mode_16_64 3
		.amdhsa_dx10_clamp 1
		.amdhsa_ieee_mode 1
		.amdhsa_fp16_overflow 0
		.amdhsa_tg_split 0
		.amdhsa_exception_fp_ieee_invalid_op 0
		.amdhsa_exception_fp_denorm_src 0
		.amdhsa_exception_fp_ieee_div_zero 0
		.amdhsa_exception_fp_ieee_overflow 0
		.amdhsa_exception_fp_ieee_underflow 0
		.amdhsa_exception_fp_ieee_inexact 0
		.amdhsa_exception_int_div_zero 0
	.end_amdhsa_kernel

; #define LAS __attribute__((address_space(3)))
; __global__ void __launch_bounds__(512, 2) mk_fwd(Args a) {
;     extern __shared__ __attribute__((aligned(16))) unsigned char lds_raw[];
;     Ctx C; C.lds = (LAS unsigned char*)lds_raw; C.wave = __builtin_amdgcn_readfirstlane((int)threadIdx.x >> 6);
amdhsa.kernels:
  - .agpr_count:     0
    .args:
      - .offset:         0
        .size:           176
        .value_kind:     by_value
      - .offset:         176
        .size:           4
        .value_kind:     hidden_block_count_x
      - .offset:         180
        .size:           4
        .value_kind:     hidden_block_count_y
      - .offset:         184
        .size:           4
        .value_kind:     hidden_block_count_z
      - .offset:         188
        .size:           2
        .value_kind:     hidden_group_size_x
      - .offset:         190
        .size:           2
        .value_kind:     hidden_group_size_y
      - .offset:         192
        .size:           2
        .value_kind:     hidden_group_size_z
      - .offset:         194
        .size:           2
        .value_kind:     hidden_remainder_x
      - .offset:         196
        .size:           2
        .value_kind:     hidden_remainder_y
      - .offset:         198
        .size:           2
        .value_kind:     hidden_remainder_z
      - .offset:         216
        .size:           8
        .value_kind:     hidden_global_offset_x
      - .offset:         224
        .size:           8
        .value_kind:     hidden_global_offset_y
      - .offset:         232
        .size:           8
        .value_kind:     hidden_global_offset_z
      - .offset:         240
        .size:           2
        .value_kind:     hidden_grid_dims
      - .offset:         264
        .size:           8
        .value_kind:     hidden_multigrid_sync_arg
      - .offset:         296
        .size:           4
        .value_kind:     hidden_dynamic_lds_size
    .group_segment_fixed_size: 16384
    .kernarg_segment_align: 8
    .kernarg_segment_size: 432
    .language:       OpenCL C
    .language_version:
      - 2
      - 0
    .max_flat_workgroup_size: 512
    .name:           _Z6mk_fwd4Args
    .private_segment_fixed_size: 0
    .sgpr_count:     106
    .sgpr_spill_count: 278
    .symbol:         _Z6mk_fwd4Args.kd
    .uniform_work_group_size: 1
    .uses_dynamic_stack: false
    .vgpr_count:     250
    .vgpr_spill_count: 0
    .wavefront_size: 64
